# v14: attention prefetches the next item's key/value tiles 0,1 into idle score registers during the last tile
# speedup vs baseline: 1.0122x; 1.0122x over previous
; __device__ __forceinline__ int v_st(int k, int c) { const int kk = (k & ~0xC) | ((k & 4) << 1) | ((k & 8) >> 1); return ((kk >> 3) * 4 + (c >> 5)) * 512 + ((kk & 7) * 32 + (c & 31)) * 2; }
; __device__ __forceinline__ int v_rd_base(int lane) { return ((lane & 3) << 3) | (((lane >> 2) & 3) << 6) | (((lane >> 4) & 1) << 5) | (((lane >> 5) & 1) << 8); }
; __device__ void phase_attn(const Params& p, char* lds) {
;   unsigned char* ws = p.ws;
;   const bf16_t* Qg = (const bf16_t*)(ws + OFF_Q); const bf16_t* KVg = (const bf16_t*)(ws + OFF_KV); const bf16_t* KPg = (const bf16_t*)(ws + OFF_KPE);
;   bf16_t* G1 = (bf16_t*)(ws + OFF_G1);
;   const f32x2* rope = (const f32x2*)(ws + OFF_ROPE);
;   const int tid = threadIdx.x, wid = tid >> 6, lane = tid & 63, r32 = lane & 31, hi = lane >> 5;
;   char* V_lds = lds; char* K_lds = lds + AT_KOFF;
;   float* wsl = (float*)(lds + AT_WOFF) + wid * 64; float* li_l = wsl; float* al_l = wsl + 32;
;   const int skey = tid >> 3, sc8 = (tid & 7) * 8;
;   const int pkey = (tid & 255) >> 2, pc8 = (tid & 3) * 8;
;   const int vst = v_st(skey, sc8), kst = skey * AT_KROW + sc8 * 2, pst = pkey * AT_KROW + (64 + pc8) * 2;
;   const int vb0 = (int)(uintptr_t)V_lds + v_rd_base(lane);
;   const int nitems = NB * 16 * 32;
;   const int xcd = blockIdx.x & 7, slot = blockIdx.x >> 3, per = gridDim.x >> 3;
;   for (int it = slot; it < nitems / 8; it += per) {
;     const int pair = (it >> 5) * 8 + xcd, qblk = it & 31;
;     const int b = pair >> 4, h = pair & 15;
;     const size_t row0 = (size_t)b * TL;
;     const size_t qrow = row0 + qblk * 256 + wid * 32 + r32;
;     const bf16_t* Kh = KVg + row0 * 2048 + h * 128;
;     const bf16_t* Kp = KPg + row0 * 32;
;     float m_reg = 0.f, l_reg = 0.f;
;     f32x16 o[2];
; #pragma unroll
;     for (int dd = 0; dd < 2; ++dd)
; #pragma unroll
;       for (int r = 0; r < 16; ++r) o[dd][r] = 0.f;
;     bf16x8 qr[6];
;     {
;       const bf16_t* Qw = Qg + qrow * 1536 + h * 96 + hi * 8;
; #pragma unroll
;       for (int d0 = 0; d0 < 6; ++d0) qr[d0] = *(const bf16x8*)(Qw + d0 * 16);
;       const int t = qblk * 256 + wid * 32 + r32;
;       const f32x2* tb = rope + (hi ? (t & 63) : (t >> 6)) * 8;
;       const u32x4 x1 = *(const u32x4*)&qr[4], x2 = *(const u32x4*)&qr[5];
.LBB0_991:
	s_or_b64 exec, exec, s[4:5]
	s_cmpk_gt_u32 s3, 0xfff
	s_waitcnt vmcnt(7)
	v_and_b32_e32 v128, 56, v183
	v_lshlrev_b32_e32 v168, 11, v161
	s_barrier
	v_and_b32_e32 v175, 63, v178
	v_and_b32_e32 v183, 31, v178
	v_lshrrev_b32_e32 v228, 5, v175
	v_readfirstlane_b32 s14, v178
	v_lshrrev_b32_e32 v229, 3, v178
	v_and_b32_e32 v230, 7, v178
	s_lshr_b32 s14, s14, 6
	s_lshr_b32 s15, s14, 2
	s_and_b32 s43, s3, 7
	s_mov_b32 s23, 0x453a4f54
	v_lshlrev_b32_e32 v129, 4, v230
	v_lshl_or_b32 v129, v229, 12, v129
	v_mul_u32_u24_e32 v167, 0xd0, v229
	v_lshl_add_u32 v167, v230, 4, v167
	v_add_u32_e32 v167, 0x10000, v167
	v_lshrrev_b32_e32 v131, 3, v229
	v_lshlrev_b32_e32 v131, 11, v131
	v_lshrrev_b32_e32 v174, 2, v230
	v_lshl_or_b32 v131, v174, 9, v131
	v_and_b32_e32 v174, 7, v229
	v_lshl_or_b32 v131, v174, 6, v131
	v_and_b32_e32 v174, 3, v178
	v_lshl_or_b32 v131, v174, 4, v131
	v_bfe_u32 v229, v178, 2, 6
	v_lshlrev_b32_e32 v130, 4, v174
	v_lshl_or_b32 v130, v229, 6, v130
	v_mul_u32_u24_e32 v169, 0xd0, v229
	v_lshl_add_u32 v169, v174, 4, v169
	v_add_u32_e32 v169, 0x10080, v169
	v_mul_u32_u24_e32 v170, 0xd0, v183
	v_lshl_add_u32 v170, v228, 4, v170
	v_add_u32_e32 v170, 0x10000, v170
	v_and_b32_e32 v174, 3, v175
	v_lshlrev_b32_e32 v174, 3, v174
	v_mov_b32_e32 v171, v174
	v_bfe_u32 v174, v175, 2, 2
	v_lshl_or_b32 v171, v174, 6, v171
	v_bfe_u32 v174, v175, 4, 1
	v_lshl_or_b32 v171, v174, 5, v171
	v_lshl_or_b32 v171, v228, 8, v171
	s_lshl_b32 s16, s14, 5
	v_add_u32_e32 v174, s16, v183
	v_mul_u32_u24_e32 v234, 0xc00, v174
	v_lshl_add_u32 v234, v228, 4, v234
	v_lshlrev_b32_e32 v235, 2, v228
	v_add_u32_e32 v235, s16, v235
	v_lshlrev_b32_e32 v235, 11, v235
	v_lshl_add_u32 v235, v183, 1, v235
	s_lshl_b32 s17, s14, 8
	s_add_i32 s17, s17, 0x1d000
	v_lshl_add_u32 v244, v183, 2, s17
	v_lshl_add_u32 v245, v228, 4, s17
	s_add_u32 s34, s86, 0x3d796000
	s_addc_u32 s35, s87, 0
	s_lshr_b32 s12, s3, 3
	s_mov_b32 s19, s12
	s_lshr_b32 s16, s19, 5
	s_lshl_b32 s16, s16, 3
	s_add_i32 s16, s16, s43
	s_lshr_b32 s22, s16, 4
	s_and_b32 s21, s16, 15
	s_mul_i32 s17, s22, 0x2100000
	s_lshl_b32 s18, s21, 8
	s_add_i32 s17, s17, s18
	s_add_u32 s17, s17, 0x29400000
	s_add_u32 s4, s86, s17
	s_addc_u32 s5, s87, 0
	s_mul_i32 s17, s22, 0x84000
	s_add_u32 s17, s17, 0x1de80000
	s_add_u32 s6, s86, s17
	s_addc_u32 s7, s87, 0
	global_load_dwordx4 v[32:35], v129, s[4:5]
	global_load_dwordx4 v[36:39], v129, s[4:5] offset:128
	global_load_dwordx4 v[40:43], v130, s[6:7]
	s_add_u32 s4, s4, 0x40000
	s_addc_u32 s5, s5, 0
	s_add_u32 s6, s6, 0x1000
	s_addc_u32 s7, s7, 0
	global_load_dwordx4 v[44:47], v129, s[4:5]
	global_load_dwordx4 v[48:51], v129, s[4:5] offset:128
	global_load_dwordx4 v[52:55], v130, s[6:7]
	s_add_u32 s4, s4, 0x40000
	s_addc_u32 s5, s5, 0
	s_add_u32 s6, s6, 0x1000
	s_addc_u32 s7, s7, 0
	s_waitcnt vmcnt(0)
; __device__ __forceinline__ unsigned cvtpk(float lo, float hi) { f32x2 v = {lo, hi}; bf16x2_t b = __builtin_convertvector(v, bf16x2_t); return *(unsigned*)&b; }
; __device__ __forceinline__ float lo16(unsigned w) { return __uint_as_float(w << 16); }
; __device__ __forceinline__ float hi16(unsigned w) { return __uint_as_float(w & 0xffff0000u); }
; #define SWAIT() asm volatile("s_waitcnt vmcnt(3)" ::: "memory")
; __device__ void phase_attn(const Params& p, char* lds) {
;     ...
;   for (int it = slot; it < nitems / 8; it += per) {
;     const int pair = (it >> 5) * 8 + xcd, qblk = it & 31;
;     const int b = pair >> 4, h = pair & 15;
;     const size_t row0 = (size_t)b * TL;
;     const size_t qrow = row0 + qblk * 256 + wid * 32 + r32;
;     const bf16_t* Kh = KVg + row0 * 2048 + h * 128;
;     const bf16_t* Kp = KPg + row0 * 32;
;     float m_reg = 0.f, l_reg = 0.f;
;     f32x16 o[2];
; #pragma unroll
;     for (int dd = 0; dd < 2; ++dd)
; #pragma unroll
;       for (int r = 0; r < 16; ++r) o[dd][r] = 0.f;
;     bf16x8 qr[6];
;     {
;       const bf16_t* Qw = Qg + qrow * 1536 + h * 96 + hi * 8;
; #pragma unroll
;       for (int d0 = 0; d0 < 6; ++d0) qr[d0] = *(const bf16x8*)(Qw + d0 * 16);
;       const int t = qblk * 256 + wid * 32 + r32;
;       const f32x2* tb = rope + (hi ? (t & 63) : (t >> 6)) * 8;
;       const u32x4 x1 = *(const u32x4*)&qr[4], x2 = *(const u32x4*)&qr[5];
;       u32x4 n1, n2;
; #pragma unroll
;       for (int q = 0; q < 4; ++q) {
;         const f32x2 csA = tb[2 * q], csB = tb[2 * q + 1];
;         const float a0 = lo16(x1[q]), a1 = hi16(x1[q]), b0 = lo16(x2[q]), b1 = hi16(x2[q]);
;         n1[q] = cvtpk(a0 * csA[0] - b0 * csA[1], a1 * csB[0] - b1 * csB[1]);
;         n2[q] = cvtpk(a0 * csA[1] + b0 * csA[0], a1 * csB[1] + b1 * csB[0]);
;       }
;       qr[4] = *(bf16x8*)&n1; qr[5] = *(bf16x8*)&n2;
;     }
;     struct { bf16x8 vs, ks, ps; } sr_[2];
;     ...
;     f32x16 pA0, pA1, pB0, pB1; float alA, alB; bf16x8 pa0, pa1, pa2, pa3;
;     constexpr int NT = TL / 64;
;     SLOAD(0, 0); asm volatile("s_waitcnt vmcnt(0)" ::: "memory"); SWRITE(0, 0); __syncthreads();
;     at_qkt(pA0, pA1, K_lds, qr, r32, hi, 0.f); at_partialSM(pA0, pA1, m_reg, alA, true);
;     SLOAD(1, 64); SLOAD(0, 128);
;     SWAIT(); SWRITE(1, 1); __syncthreads();
.Lat_item:
	s_lshr_b32 s16, s12, 5
	s_lshl_b32 s16, s16, 3
	s_add_i32 s16, s16, s43
	s_and_b32 s20, s12, 31
	s_lshr_b32 s22, s16, 4
	s_and_b32 s21, s16, 15
	s_mul_i32 s17, s22, 0x2100
	s_lshl_b32 s18, s20, 8
	s_add_i32 s17, s17, s18
	s_mul_i32 s18, s17, 0xc00
	s_mul_i32 s19, s21, 0xc0
	s_add_i32 s18, s18, s19
	s_add_u32 s18, s18, 0x8400000
	s_add_u32 s10, s86, s18
	s_addc_u32 s11, s87, 0
	s_lshl_b32 s18, s17, 11
	s_lshl_b32 s19, s21, 7
	s_add_i32 s18, s18, s19
	s_add_u32 s18, s18, 0x21000000
	s_add_u32 s28, s86, s18
	s_addc_u32 s29, s87, 0
	global_load_dwordx4 v[80:83], v234, s[10:11] offset:0
	global_load_dwordx4 v[84:87], v234, s[10:11] offset:32
	global_load_dwordx4 v[88:91], v234, s[10:11] offset:64
	global_load_dwordx4 v[92:95], v234, s[10:11] offset:96
	global_load_dwordx4 v[96:99], v234, s[10:11] offset:128
	global_load_dwordx4 v[100:103], v234, s[10:11] offset:160
	s_and_b32 s16, s14, 1
	s_lshl_b32 s16, s16, 5
	v_and_b32_e32 v183, 31, v178
	v_add_u32_e32 v183, s16, v183
	v_lshlrev_b32_e32 v183, 6, v183
	s_lshl_b32 s16, s20, 2
	s_lshr_b32 s17, s14, 1
	s_add_i32 s16, s16, s17
	s_lshl_b32 s16, s16, 6
	v_mov_b32_e32 v228, s16
	v_and_b32_e32 v229, 32, v178
	v_cmp_ne_u32_e32 vcc, 0, v229
	s_nop 1
	v_cndmask_b32_e32 v183, v228, v183, vcc
	global_load_dwordx4 v[200:203], v183, s[34:35] offset:0
	global_load_dwordx4 v[204:207], v183, s[34:35] offset:16
	global_load_dwordx4 v[208:211], v183, s[34:35] offset:32
	global_load_dwordx4 v[212:215], v183, s[34:35] offset:48
	s_barrier
	ds_write_b128 v167, v[32:35] offset:0
	ds_write_b128 v131, v[36:39] offset:0
	ds_write_b128 v169, v[40:43] offset:0
	ds_write_b128 v167, v[44:47] offset:13312
	ds_write_b128 v131, v[48:51] offset:16384
	ds_write_b128 v169, v[52:55] offset:13312
	s_waitcnt lgkmcnt(0)
	global_load_dwordx4 v[120:123], v129, s[4:5]
	global_load_dwordx4 v[124:127], v129, s[4:5] offset:128
	global_load_dwordx4 v[132:135], v130, s[6:7]
	s_add_u32 s4, s4, 0x40000
	s_addc_u32 s5, s5, 0
	s_add_u32 s6, s6, 0x1000
	s_addc_u32 s7, s7, 0
	s_waitcnt vmcnt(3)
	v_lshlrev_b32_e32 v175, 16, v96
	v_and_b32_e32 v183, 0xffff0000, v96
	v_lshlrev_b32_e32 v228, 16, v100
	v_and_b32_e32 v229, 0xffff0000, v100
	v_mul_f32_e32 v230, v228, v201
	v_mul_f32_e32 v174, v229, v203
	v_fma_f32 v230, v175, v200, -v230
	v_fma_f32 v174, v183, v202, -v174
	v_mul_f32_e32 v175, v175, v201
	v_mul_f32_e32 v183, v183, v203
	v_fma_f32 v175, v228, v200, v175
	v_fma_f32 v183, v229, v202, v183
	v_cvt_pk_bf16_f32 v96, v230, v174
	v_cvt_pk_bf16_f32 v100, v175, v183
	v_lshlrev_b32_e32 v175, 16, v97
	v_and_b32_e32 v183, 0xffff0000, v97
	v_lshlrev_b32_e32 v228, 16, v101
	v_and_b32_e32 v229, 0xffff0000, v101
	v_mul_f32_e32 v230, v228, v205
	v_mul_f32_e32 v174, v229, v207
	v_fma_f32 v230, v175, v204, -v230
	v_fma_f32 v174, v183, v206, -v174
	v_mul_f32_e32 v175, v175, v205
	v_mul_f32_e32 v183, v183, v207
	v_fma_f32 v175, v228, v204, v175
	v_fma_f32 v183, v229, v206, v183
	v_cvt_pk_bf16_f32 v97, v230, v174
	v_cvt_pk_bf16_f32 v101, v175, v183
	v_lshlrev_b32_e32 v175, 16, v98
	v_and_b32_e32 v183, 0xffff0000, v98
	v_lshlrev_b32_e32 v228, 16, v102
	v_and_b32_e32 v229, 0xffff0000, v102
	v_mul_f32_e32 v230, v228, v209
	v_mul_f32_e32 v174, v229, v211
	v_fma_f32 v230, v175, v208, -v230
	v_fma_f32 v174, v183, v210, -v174
	v_mul_f32_e32 v175, v175, v209
	v_mul_f32_e32 v183, v183, v211
	v_fma_f32 v175, v228, v208, v175
	v_fma_f32 v183, v229, v210, v183
	v_cvt_pk_bf16_f32 v98, v230, v174
	v_cvt_pk_bf16_f32 v102, v175, v183
	v_lshlrev_b32_e32 v175, 16, v99
	v_and_b32_e32 v183, 0xffff0000, v99
	v_lshlrev_b32_e32 v228, 16, v103
	v_and_b32_e32 v229, 0xffff0000, v103
	v_mul_f32_e32 v230, v228, v213
	v_mul_f32_e32 v174, v229, v215
	v_fma_f32 v230, v175, v212, -v230
	v_fma_f32 v174, v183, v214, -v174
	v_mul_f32_e32 v175, v175, v213
	v_mul_f32_e32 v183, v183, v215
	v_fma_f32 v175, v228, v212, v175
	v_fma_f32 v183, v229, v214, v183
	v_cvt_pk_bf16_f32 v99, v230, v174
	v_cvt_pk_bf16_f32 v103, v175, v183
	v_mov_b32_e32 v0, 0
	v_mov_b32_e32 v1, 0
	v_mov_b32_e32 v2, 0
	v_mov_b32_e32 v3, 0
	v_mov_b32_e32 v4, 0
	v_mov_b32_e32 v5, 0
	v_mov_b32_e32 v6, 0
	v_mov_b32_e32 v7, 0
	v_mov_b32_e32 v8, 0
	v_mov_b32_e32 v9, 0
	v_mov_b32_e32 v10, 0
	v_mov_b32_e32 v11, 0
	v_mov_b32_e32 v12, 0
	v_mov_b32_e32 v13, 0
	v_mov_b32_e32 v14, 0
	v_mov_b32_e32 v15, 0
	v_mov_b32_e32 v16, 0
	v_mov_b32_e32 v17, 0
	v_mov_b32_e32 v18, 0
	v_mov_b32_e32 v19, 0
	v_mov_b32_e32 v20, 0
	v_mov_b32_e32 v21, 0
	v_mov_b32_e32 v22, 0
	v_mov_b32_e32 v23, 0
	v_mov_b32_e32 v24, 0
	v_mov_b32_e32 v25, 0
	v_mov_b32_e32 v26, 0
	v_mov_b32_e32 v27, 0
	v_mov_b32_e32 v28, 0
	v_mov_b32_e32 v29, 0
	v_mov_b32_e32 v30, 0
	v_mov_b32_e32 v31, 0
	v_mov_b32_e32 v173, 0
	s_barrier
	ds_read_b128 v[184:187], v170 offset:0
	ds_read_b128 v[188:191], v170 offset:6656
	ds_read_b128 v[192:195], v170 offset:32
	ds_read_b128 v[196:199], v170 offset:6688
	s_cmp_eq_u32 s15, 0
	s_cbranch_scc1 .Lat_nostag
	s_barrier

; __device__ __forceinline__ int crow(int r, int hi) { return (r & 3) + 8 * (r >> 2) + 4 * hi; }
; #define MFMA(a, b, c) __builtin_amdgcn_mfma_f32_32x32x16_bf16((a), (b), (c), 0, 0, 0)
; #define SBAR() __builtin_amdgcn_sched_barrier(0)
; #define RESC(a) do { if (__any((a) < 1.f)) { if (hi == 0) al_l[r32] = (a); asm volatile("s_waitcnt lgkmcnt(0)" ::: "memory"); \
;     _Pragma("unroll") for (int dd = 0; dd < 2; ++dd) _Pragma("unroll") for (int r = 0; r < 16; ++r) o[dd][r] *= al_l[crow(r, hi)]; } } while (0)
; template <int D0> __device__ __forceinline__ void pv_one(f32x16& od, int vb, bf16x8 pa0, bf16x8 pa1, bf16x8 pa2, bf16x8 pa3) {
;   const s16x4 l0 = tr_read<v_rd_off(D0, 0, 0)>(vb), h0 = tr_read<v_rd_off(D0, 0, 1)>(vb), l1 = tr_read<v_rd_off(D0, 1, 0)>(vb), h1 = tr_read<v_rd_off(D0, 1, 1)>(vb);
;   const s16x4 l2 = tr_read<v_rd_off(D0, 2, 0)>(vb), h2 = tr_read<v_rd_off(D0, 2, 1)>(vb), l3 = tr_read<v_rd_off(D0, 3, 0)>(vb), h3 = tr_read<v_rd_off(D0, 3, 1)>(vb);
;   asm volatile("s_waitcnt lgkmcnt(0)" ::: "memory"); SBAR();
;     ...
;   od = MFMA(pa0, PK(l0, h0), od);
;   od = MFMA(pa1, PK(l1, h1), od);
;   od = MFMA(pa2, PK(l2, h2), od);
;   od = MFMA(pa3, PK(l3, h3), od);
;     ...
; }
; __device__ __forceinline__ void pv_d0(f32x16* o, int vb, bf16x8 pa0, bf16x8 pa1, bf16x8 pa2, bf16x8 pa3) {
;   pv_one<0>(o[0], vb, pa0, pa1, pa2, pa3); pv_one<1>(o[1], vb, pa0, pa1, pa2, pa3);
; __device__ void phase_attn(const Params& p, char* lds) {
;     ...
;     SBAR(); at_qkt(pB0, pB1, K_lds + AT_SHMK, qr, r32, hi, -m_reg);
;     at_finishSM(pA0, pA1, alA, l_reg, pa0, pa1, pa2, pa3); SBAR();
;     pv_d0(o, vb0, pa0, pa1, pa2, pa3); at_partialSM(pB0, pB1, m_reg, alB, false);
;     __syncthreads(); RESC(alB);
;     at_finishSM(pB0, pB1, alB, l_reg, pa0, pa1, pa2, pa3); SBAR();
;     pv_d0(o, vb0 + AT_SHMV, pa0, pa1, pa2, pa3);
;     if (hi == 0) li_l[r32] = l_reg;
;     asm volatile("s_waitcnt lgkmcnt(0)" ::: "memory");
;     float rli[16];
; #pragma unroll
;     for (int r = 0; r < 16; ++r) rli[r] = __builtin_amdgcn_rcpf(li_l[crow(r, hi)]);
.Lat_rare_t131_back:
	v_add_f32_e32 v173, v173, v175
	v_cvt_pk_bf16_f32 v104, v32, v33
	v_cvt_pk_bf16_f32 v105, v34, v35
	v_cvt_pk_bf16_f32 v106, v36, v37
	v_cvt_pk_bf16_f32 v107, v38, v39
	v_cvt_pk_bf16_f32 v108, v40, v41
	v_cvt_pk_bf16_f32 v109, v42, v43
	v_cvt_pk_bf16_f32 v110, v44, v45
	v_cvt_pk_bf16_f32 v111, v46, v47
	v_cvt_pk_bf16_f32 v112, v48, v49
	v_cvt_pk_bf16_f32 v113, v50, v51
	v_cvt_pk_bf16_f32 v114, v52, v53
	v_cvt_pk_bf16_f32 v115, v54, v55
	v_cvt_pk_bf16_f32 v116, v56, v57
	v_cvt_pk_bf16_f32 v117, v58, v59
	v_cvt_pk_bf16_f32 v118, v60, v61
	v_cvt_pk_bf16_f32 v119, v62, v63
	s_add_i32 s19, s12, s33
	s_lshr_b32 s16, s19, 5
	s_lshl_b32 s16, s16, 3
	s_add_i32 s16, s16, s43
	s_lshr_b32 s22, s16, 4
	s_and_b32 s21, s16, 15
	s_mul_i32 s17, s22, 0x2100000
	s_lshl_b32 s18, s21, 8
	s_add_i32 s17, s17, s18
	s_add_u32 s17, s17, 0x29400000
	s_add_u32 s4, s86, s17
	s_addc_u32 s5, s87, 0
	s_mul_i32 s17, s22, 0x84000
	s_add_u32 s17, s17, 0x1de80000
	s_add_u32 s6, s86, s17
	s_addc_u32 s7, s87, 0
	global_load_dwordx4 v[32:35], v129, s[4:5]
	global_load_dwordx4 v[36:39], v129, s[4:5] offset:128
	global_load_dwordx4 v[40:43], v130, s[6:7]
	s_add_u32 s4, s4, 0x40000
	s_addc_u32 s5, s5, 0
	s_add_u32 s6, s6, 0x1000
	s_addc_u32 s7, s7, 0
	global_load_dwordx4 v[44:47], v129, s[4:5]
	global_load_dwordx4 v[48:51], v129, s[4:5] offset:128
	global_load_dwordx4 v[52:55], v130, s[6:7]
	s_add_u32 s4, s4, 0x40000
	s_addc_u32 s5, s5, 0
	s_add_u32 s6, s6, 0x1000
	s_addc_u32 s7, s7, 0
	s_barrier
	ds_read_b64_tr_b16 v[148:149], v171 offset:49152
	ds_read_b64_tr_b16 v[150:151], v171 offset:51200
	ds_read_b64_tr_b16 v[152:153], v171 offset:53248
	ds_read_b64_tr_b16 v[154:155], v171 offset:55296
	ds_read_b64_tr_b16 v[156:157], v171 offset:57344
	ds_read_b64_tr_b16 v[158:159], v171 offset:59392
	ds_read_b64_tr_b16 v[216:217], v171 offset:61440
	ds_read_b64_tr_b16 v[218:219], v171 offset:63488
	ds_read_b64_tr_b16 v[220:221], v171 offset:49664
	ds_read_b64_tr_b16 v[222:223], v171 offset:51712
	ds_read_b64_tr_b16 v[224:225], v171 offset:53760
	ds_read_b64_tr_b16 v[226:227], v171 offset:55808
	s_waitcnt lgkmcnt(10)
	v_mfma_f32_32x32x16_bf16 v[0:15], v[104:107], v[148:151], v[0:15]
	s_waitcnt lgkmcnt(8)
	v_mfma_f32_32x32x16_bf16 v[0:15], v[108:111], v[152:155], v[0:15]
	ds_read_b64_tr_b16 v[236:237], v171 offset:57856
	ds_read_b64_tr_b16 v[238:239], v171 offset:59904
	ds_read_b64_tr_b16 v[240:241], v171 offset:61952
	ds_read_b64_tr_b16 v[242:243], v171 offset:64000
	s_waitcnt lgkmcnt(10)
	v_mfma_f32_32x32x16_bf16 v[0:15], v[112:115], v[156:159], v[0:15]
	s_waitcnt lgkmcnt(8)
	v_mfma_f32_32x32x16_bf16 v[0:15], v[116:119], v[216:219], v[0:15]
	s_waitcnt lgkmcnt(6)
	v_mfma_f32_32x32x16_bf16 v[16:31], v[104:107], v[220:223], v[16:31]
	s_waitcnt lgkmcnt(4)
	v_mfma_f32_32x32x16_bf16 v[16:31], v[108:111], v[224:227], v[16:31]
	s_waitcnt lgkmcnt(2)
	v_mfma_f32_32x32x16_bf16 v[16:31], v[112:115], v[236:239], v[16:31]
	s_waitcnt lgkmcnt(0)
	v_mfma_f32_32x32x16_bf16 v[16:31], v[116:119], v[240:243], v[16:31]
	s_cmp_lg_u32 s15, 0
	s_cbranch_scc1 .Lat_nobal
	s_barrier
.Lat_nobal:
	v_mov_b32_e32 v175, v173
	s_nop 1
	v_permlane32_swap_b32_e32 v173, v175
	v_add_f32_e32 v173, v173, v175
	ds_write_b32 v244, v173 offset:128
	s_waitcnt lgkmcnt(0)
	ds_read_b128 v[184:187], v245 offset:128
	ds_read_b128 v[188:191], v245 offset:160
	ds_read_b128 v[192:195], v245 offset:192
	ds_read_b128 v[196:199], v245 offset:224
	s_waitcnt lgkmcnt(0)
	v_rcp_f32_e32 v184, v184
	v_rcp_f32_e32 v185, v185
	v_rcp_f32_e32 v186, v186
	v_rcp_f32_e32 v187, v187
	v_rcp_f32_e32 v188, v188
	v_rcp_f32_e32 v189, v189
	v_rcp_f32_e32 v190, v190
	v_rcp_f32_e32 v191, v191
	v_rcp_f32_e32 v192, v192
	v_rcp_f32_e32 v193, v193
	v_rcp_f32_e32 v194, v194
	v_rcp_f32_e32 v195, v195
	v_rcp_f32_e32 v196, v196
	v_rcp_f32_e32 v197, v197
	v_rcp_f32_e32 v198, v198
	v_rcp_f32_e32 v199, v199
	v_mul_f32_e32 v0, v0, v184
	v_mul_f32_e32 v16, v16, v184
	v_mul_f32_e32 v1, v1, v185
	v_mul_f32_e32 v17, v17, v185
	v_mul_f32_e32 v2, v2, v186
	v_mul_f32_e32 v18, v18, v186
	v_mul_f32_e32 v3, v3, v187
	v_mul_f32_e32 v19, v19, v187
	v_mul_f32_e32 v4, v4, v188
	v_mul_f32_e32 v20, v20, v188
	v_mul_f32_e32 v5, v5, v189
	v_mul_f32_e32 v21, v21, v189
	v_mul_f32_e32 v6, v6, v190
	v_mul_f32_e32 v22, v22, v190
	v_mul_f32_e32 v7, v7, v191
	v_mul_f32_e32 v23, v23, v191
	v_mul_f32_e32 v8, v8, v192
	v_mul_f32_e32 v24, v24, v192
	v_mul_f32_e32 v9, v9, v193
	v_mul_f32_e32 v25, v25, v193
	v_mul_f32_e32 v10, v10, v194
	v_mul_f32_e32 v26, v26, v194
	v_mul_f32_e32 v11, v11, v195
	v_mul_f32_e32 v27, v27, v195
	v_mul_f32_e32 v12, v12, v196
	v_mul_f32_e32 v28, v28, v196
	v_mul_f32_e32 v13, v13, v197
	v_mul_f32_e32 v29, v29, v197
	v_mul_f32_e32 v14, v14, v198
	v_mul_f32_e32 v30, v30, v198
	v_mul_f32_e32 v15, v15, v199
	v_mul_f32_e32 v31, v31, v199
	s_waitcnt vmcnt(0)
; __device__ __forceinline__ float bf2f(bf16_t u) { return __uint_as_float(((unsigned)u) << 16); }
; __device__ __forceinline__ bf16_t f2bf(float f) { return (bf16_t)(cvtpk(f, 0.f) & 0xffffu); }
; __device__ __forceinline__ int crow(int r, int hi) { return (r & 3) + 8 * (r >> 2) + 4 * hi; }
; __device__ __forceinline__ float sigmoidf_(float x) { return __builtin_amdgcn_rcpf(1.f + __expf(-x)); }
; __device__ void phase_attn(const Params& p, char* lds) {
;     ...
;     bf16_t* Gw = G1 + (row0 + qblk * 256 + wid * 32) * 1024 + h * 64 + r32;
;     bf16_t gin[32];
; #pragma unroll
;     for (int r = 0; r < 16; ++r) { gin[2 * r] = Gw[(size_t)crow(r, hi) * 1024]; gin[2 * r + 1] = Gw[(size_t)crow(r, hi) * 1024 + 32]; }
;     asm volatile("" ::: "memory");
; #pragma unroll
;     for (int r = 0; r < 16; ++r) {
;       const int orow = crow(r, hi);
; #pragma unroll
;       for (int d0 = 0; d0 < 2; ++d0) {
;         const float gt = bf2f(gin[2 * r + d0]);
;         Gw[(size_t)orow * 1024 + d0 * 32] = f2bf(o[d0][r] * rli[r] * gt * sigmoidf_(gt));
;       }
;     }
	v_lshlrev_b32_e32 v120, 16, v120
	v_lshlrev_b32_e32 v121, 16, v121
	v_lshlrev_b32_e32 v122, 16, v122
	v_lshlrev_b32_e32 v123, 16, v123
	v_lshlrev_b32_e32 v124, 16, v124
	v_lshlrev_b32_e32 v125, 16, v125
	v_lshlrev_b32_e32 v126, 16, v126
	v_lshlrev_b32_e32 v127, 16, v127
	v_mul_f32_e32 v64, 0xbfb8aa3b, v120
	v_mul_f32_e32 v65, 0xbfb8aa3b, v121
	v_mul_f32_e32 v66, 0xbfb8aa3b, v122
	v_mul_f32_e32 v67, 0xbfb8aa3b, v123
	v_mul_f32_e32 v68, 0xbfb8aa3b, v124
	v_mul_f32_e32 v69, 0xbfb8aa3b, v125
	v_mul_f32_e32 v70, 0xbfb8aa3b, v126
	v_mul_f32_e32 v71, 0xbfb8aa3b, v127
	v_exp_f32_e32 v64, v64
	v_exp_f32_e32 v65, v65
	v_exp_f32_e32 v66, v66
	v_exp_f32_e32 v67, v67
	v_exp_f32_e32 v68, v68
	v_exp_f32_e32 v69, v69
	v_exp_f32_e32 v70, v70
	v_exp_f32_e32 v71, v71
	v_add_f32_e32 v64, 1.0, v64
	v_add_f32_e32 v65, 1.0, v65
	v_add_f32_e32 v66, 1.0, v66
	v_add_f32_e32 v67, 1.0, v67
	v_add_f32_e32 v68, 1.0, v68
	v_add_f32_e32 v69, 1.0, v69
	v_add_f32_e32 v70, 1.0, v70
	v_add_f32_e32 v71, 1.0, v71
	v_rcp_f32_e32 v64, v64
	v_rcp_f32_e32 v65, v65
	v_rcp_f32_e32 v66, v66
	v_rcp_f32_e32 v67, v67
	v_rcp_f32_e32 v68, v68
	v_rcp_f32_e32 v69, v69
	v_rcp_f32_e32 v70, v70
	v_rcp_f32_e32 v71, v71
	v_mul_f32_e32 v0, v0, v120
	v_mul_f32_e32 v16, v16, v121
	v_mul_f32_e32 v1, v1, v122
	v_mul_f32_e32 v17, v17, v123
	v_mul_f32_e32 v2, v2, v124
	v_mul_f32_e32 v18, v18, v125
	v_mul_f32_e32 v3, v3, v126
	v_mul_f32_e32 v19, v19, v127
	v_mul_f32_e32 v0, v0, v64
	v_mul_f32_e32 v16, v16, v65
	v_mul_f32_e32 v1, v1, v66
	v_mul_f32_e32 v17, v17, v67
	v_mul_f32_e32 v2, v2, v68
	v_mul_f32_e32 v18, v18, v69
	v_mul_f32_e32 v3, v3, v70
	v_mul_f32_e32 v19, v19, v71
	v_cvt_pk_bf16_f32 v0, v0, v0
	v_cvt_pk_bf16_f32 v16, v16, v16
	v_cvt_pk_bf16_f32 v1, v1, v1
	v_cvt_pk_bf16_f32 v17, v17, v17
	v_cvt_pk_bf16_f32 v2, v2, v2
	v_cvt_pk_bf16_f32 v18, v18, v18
	v_cvt_pk_bf16_f32 v3, v3, v3
	v_cvt_pk_bf16_f32 v19, v19, v19
	s_add_u32 s8, s28, 0x0
	s_addc_u32 s9, s29, 0
	global_store_short v235, v0, s[8:9] offset:0
	global_store_short v235, v16, s[8:9] offset:64
	global_store_short v235, v1, s[8:9] offset:2048
	global_store_short v235, v17, s[8:9] offset:2112
	s_add_u32 s8, s28, 0x1000
	s_addc_u32 s9, s29, 0
	global_store_short v235, v2, s[8:9] offset:0
	global_store_short v235, v18, s[8:9] offset:64
	global_store_short v235, v3, s[8:9] offset:2048
	global_store_short v235, v19, s[8:9] offset:2112
	v_lshlrev_b32_e32 v132, 16, v132
	v_lshlrev_b32_e32 v133, 16, v133
	v_lshlrev_b32_e32 v134, 16, v134
	v_lshlrev_b32_e32 v135, 16, v135
	v_lshlrev_b32_e32 v136, 16, v136
	v_lshlrev_b32_e32 v137, 16, v137
	v_lshlrev_b32_e32 v138, 16, v138
	v_lshlrev_b32_e32 v139, 16, v139
	v_mul_f32_e32 v64, 0xbfb8aa3b, v132
	v_mul_f32_e32 v65, 0xbfb8aa3b, v133
	v_mul_f32_e32 v66, 0xbfb8aa3b, v134
	v_mul_f32_e32 v67, 0xbfb8aa3b, v135
	v_mul_f32_e32 v68, 0xbfb8aa3b, v136
	v_mul_f32_e32 v69, 0xbfb8aa3b, v137
	v_mul_f32_e32 v70, 0xbfb8aa3b, v138
	v_mul_f32_e32 v71, 0xbfb8aa3b, v139
	v_exp_f32_e32 v64, v64
	v_exp_f32_e32 v65, v65
	v_exp_f32_e32 v66, v66
	v_exp_f32_e32 v67, v67
	v_exp_f32_e32 v68, v68
	v_exp_f32_e32 v69, v69
	v_exp_f32_e32 v70, v70
	v_exp_f32_e32 v71, v71
	v_add_f32_e32 v64, 1.0, v64
	v_add_f32_e32 v65, 1.0, v65
	v_add_f32_e32 v66, 1.0, v66
	v_add_f32_e32 v67, 1.0, v67
	v_add_f32_e32 v68, 1.0, v68
	v_add_f32_e32 v69, 1.0, v69
	v_add_f32_e32 v70, 1.0, v70
	v_add_f32_e32 v71, 1.0, v71
	v_rcp_f32_e32 v64, v64
	v_rcp_f32_e32 v65, v65
	v_rcp_f32_e32 v66, v66
	v_rcp_f32_e32 v67, v67
	v_rcp_f32_e32 v68, v68
	v_rcp_f32_e32 v69, v69
	v_rcp_f32_e32 v70, v70
	v_rcp_f32_e32 v71, v71
	v_mul_f32_e32 v4, v4, v132
	v_mul_f32_e32 v20, v20, v133
	v_mul_f32_e32 v5, v5, v134
	v_mul_f32_e32 v21, v21, v135
	v_mul_f32_e32 v6, v6, v136
	v_mul_f32_e32 v22, v22, v137
	v_mul_f32_e32 v7, v7, v138
	v_mul_f32_e32 v23, v23, v139
	v_mul_f32_e32 v4, v4, v64
	v_mul_f32_e32 v20, v20, v65
	v_mul_f32_e32 v5, v5, v66
	v_mul_f32_e32 v21, v21, v67
	v_mul_f32_e32 v6, v6, v68
	v_mul_f32_e32 v22, v22, v69
	v_mul_f32_e32 v7, v7, v70
	v_mul_f32_e32 v23, v23, v71
	v_cvt_pk_bf16_f32 v4, v4, v4
	v_cvt_pk_bf16_f32 v20, v20, v20
	v_cvt_pk_bf16_f32 v5, v5, v5
	v_cvt_pk_bf16_f32 v21, v21, v21
	v_cvt_pk_bf16_f32 v6, v6, v6
	v_cvt_pk_bf16_f32 v22, v22, v22
	v_cvt_pk_bf16_f32 v7, v7, v7
	v_cvt_pk_bf16_f32 v23, v23, v23
	s_add_u32 s8, s28, 0x4000
	s_addc_u32 s9, s29, 0
	global_store_short v235, v4, s[8:9] offset:0
	global_store_short v235, v20, s[8:9] offset:64
	global_store_short v235, v5, s[8:9] offset:2048
	global_store_short v235, v21, s[8:9] offset:2112
	s_add_u32 s8, s28, 0x5000
	s_addc_u32 s9, s29, 0
	global_store_short v235, v6, s[8:9] offset:0
	global_store_short v235, v22, s[8:9] offset:64
	global_store_short v235, v7, s[8:9] offset:2048
	global_store_short v235, v23, s[8:9] offset:2112
	v_lshlrev_b32_e32 v140, 16, v140
	v_lshlrev_b32_e32 v141, 16, v141
; __device__ __forceinline__ float bf2f(bf16_t u) { return __uint_as_float(((unsigned)u) << 16); }
; __device__ __forceinline__ bf16_t f2bf(float f) { return (bf16_t)(cvtpk(f, 0.f) & 0xffffu); }
; __device__ __forceinline__ int crow(int r, int hi) { return (r & 3) + 8 * (r >> 2) + 4 * hi; }
; __device__ __forceinline__ float sigmoidf_(float x) { return __builtin_amdgcn_rcpf(1.f + __expf(-x)); }
; __device__ void phase_attn(const Params& p, char* lds) {
;     ...
; #pragma unroll
;     for (int r = 0; r < 16; ++r) {
;       const int orow = crow(r, hi);
; #pragma unroll
;       for (int d0 = 0; d0 < 2; ++d0) {
;         const float gt = bf2f(gin[2 * r + d0]);
;         Gw[(size_t)orow * 1024 + d0 * 32] = f2bf(o[d0][r] * rli[r] * gt * sigmoidf_(gt));
;       }
;     }
	v_lshlrev_b32_e32 v142, 16, v142
	v_lshlrev_b32_e32 v143, 16, v143
	v_lshlrev_b32_e32 v144, 16, v144
	v_lshlrev_b32_e32 v145, 16, v145
	v_lshlrev_b32_e32 v146, 16, v146
	v_lshlrev_b32_e32 v147, 16, v147
	v_mul_f32_e32 v64, 0xbfb8aa3b, v140
	v_mul_f32_e32 v65, 0xbfb8aa3b, v141
	v_mul_f32_e32 v66, 0xbfb8aa3b, v142
	v_mul_f32_e32 v67, 0xbfb8aa3b, v143
	v_mul_f32_e32 v68, 0xbfb8aa3b, v144
	v_mul_f32_e32 v69, 0xbfb8aa3b, v145
	v_mul_f32_e32 v70, 0xbfb8aa3b, v146
	v_mul_f32_e32 v71, 0xbfb8aa3b, v147
	v_exp_f32_e32 v64, v64
	v_exp_f32_e32 v65, v65
	v_exp_f32_e32 v66, v66
	v_exp_f32_e32 v67, v67
	v_exp_f32_e32 v68, v68
	v_exp_f32_e32 v69, v69
	v_exp_f32_e32 v70, v70
	v_exp_f32_e32 v71, v71
	v_add_f32_e32 v64, 1.0, v64
	v_add_f32_e32 v65, 1.0, v65
	v_add_f32_e32 v66, 1.0, v66
	v_add_f32_e32 v67, 1.0, v67
	v_add_f32_e32 v68, 1.0, v68
	v_add_f32_e32 v69, 1.0, v69
	v_add_f32_e32 v70, 1.0, v70
	v_add_f32_e32 v71, 1.0, v71
	v_rcp_f32_e32 v64, v64
	v_rcp_f32_e32 v65, v65
	v_rcp_f32_e32 v66, v66
	v_rcp_f32_e32 v67, v67
	v_rcp_f32_e32 v68, v68
	v_rcp_f32_e32 v69, v69
	v_rcp_f32_e32 v70, v70
	v_rcp_f32_e32 v71, v71
	v_mul_f32_e32 v8, v8, v140
	v_mul_f32_e32 v24, v24, v141
	v_mul_f32_e32 v9, v9, v142
	v_mul_f32_e32 v25, v25, v143
	v_mul_f32_e32 v10, v10, v144
	v_mul_f32_e32 v26, v26, v145
	v_mul_f32_e32 v11, v11, v146
	v_mul_f32_e32 v27, v27, v147
	v_mul_f32_e32 v8, v8, v64
	v_mul_f32_e32 v24, v24, v65
	v_mul_f32_e32 v9, v9, v66
	v_mul_f32_e32 v25, v25, v67
	v_mul_f32_e32 v10, v10, v68
	v_mul_f32_e32 v26, v26, v69
	v_mul_f32_e32 v11, v11, v70
	v_mul_f32_e32 v27, v27, v71
	v_cvt_pk_bf16_f32 v8, v8, v8
	v_cvt_pk_bf16_f32 v24, v24, v24
	v_cvt_pk_bf16_f32 v9, v9, v9
	v_cvt_pk_bf16_f32 v25, v25, v25
	v_cvt_pk_bf16_f32 v10, v10, v10
	v_cvt_pk_bf16_f32 v26, v26, v26
	v_cvt_pk_bf16_f32 v11, v11, v11
	v_cvt_pk_bf16_f32 v27, v27, v27
	s_add_u32 s8, s28, 0x8000
	s_addc_u32 s9, s29, 0
	global_store_short v235, v8, s[8:9] offset:0
	global_store_short v235, v24, s[8:9] offset:64
	global_store_short v235, v9, s[8:9] offset:2048
	global_store_short v235, v25, s[8:9] offset:2112
	s_add_u32 s8, s28, 0x9000
	s_addc_u32 s9, s29, 0
	global_store_short v235, v10, s[8:9] offset:0
	global_store_short v235, v26, s[8:9] offset:64
	global_store_short v235, v11, s[8:9] offset:2048
	global_store_short v235, v27, s[8:9] offset:2112
	v_lshlrev_b32_e32 v200, 16, v200
	v_lshlrev_b32_e32 v201, 16, v201
	v_lshlrev_b32_e32 v202, 16, v202
	v_lshlrev_b32_e32 v203, 16, v203
	v_lshlrev_b32_e32 v204, 16, v204
	v_lshlrev_b32_e32 v205, 16, v205
	v_lshlrev_b32_e32 v206, 16, v206
	v_lshlrev_b32_e32 v207, 16, v207
	v_mul_f32_e32 v64, 0xbfb8aa3b, v200
	v_mul_f32_e32 v65, 0xbfb8aa3b, v201
	v_mul_f32_e32 v66, 0xbfb8aa3b, v202
	v_mul_f32_e32 v67, 0xbfb8aa3b, v203
	v_mul_f32_e32 v68, 0xbfb8aa3b, v204
	v_mul_f32_e32 v69, 0xbfb8aa3b, v205
	v_mul_f32_e32 v70, 0xbfb8aa3b, v206
	v_mul_f32_e32 v71, 0xbfb8aa3b, v207
	v_exp_f32_e32 v64, v64
	v_exp_f32_e32 v65, v65
	v_exp_f32_e32 v66, v66
	v_exp_f32_e32 v67, v67
	v_exp_f32_e32 v68, v68
	v_exp_f32_e32 v69, v69
	v_exp_f32_e32 v70, v70
	v_exp_f32_e32 v71, v71
	v_add_f32_e32 v64, 1.0, v64
	v_add_f32_e32 v65, 1.0, v65
	v_add_f32_e32 v66, 1.0, v66
	v_add_f32_e32 v67, 1.0, v67
	v_add_f32_e32 v68, 1.0, v68
	v_add_f32_e32 v69, 1.0, v69
	v_add_f32_e32 v70, 1.0, v70
	v_add_f32_e32 v71, 1.0, v71
	v_rcp_f32_e32 v64, v64
	v_rcp_f32_e32 v65, v65
	v_rcp_f32_e32 v66, v66
	v_rcp_f32_e32 v67, v67
	v_rcp_f32_e32 v68, v68
	v_rcp_f32_e32 v69, v69
	v_rcp_f32_e32 v70, v70
	v_rcp_f32_e32 v71, v71
	v_mul_f32_e32 v12, v12, v200
	v_mul_f32_e32 v28, v28, v201
	v_mul_f32_e32 v13, v13, v202
	v_mul_f32_e32 v29, v29, v203
	v_mul_f32_e32 v14, v14, v204
	v_mul_f32_e32 v30, v30, v205
	v_mul_f32_e32 v15, v15, v206
	v_mul_f32_e32 v31, v31, v207
	v_mul_f32_e32 v12, v12, v64
	v_mul_f32_e32 v28, v28, v65
	v_mul_f32_e32 v13, v13, v66
	v_mul_f32_e32 v29, v29, v67
	v_mul_f32_e32 v14, v14, v68
	v_mul_f32_e32 v30, v30, v69
	v_mul_f32_e32 v15, v15, v70
	v_mul_f32_e32 v31, v31, v71
	v_cvt_pk_bf16_f32 v12, v12, v12
	v_cvt_pk_bf16_f32 v28, v28, v28
	v_cvt_pk_bf16_f32 v13, v13, v13
	v_cvt_pk_bf16_f32 v29, v29, v29
	v_cvt_pk_bf16_f32 v14, v14, v14
	v_cvt_pk_bf16_f32 v30, v30, v30
	v_cvt_pk_bf16_f32 v15, v15, v15
	v_cvt_pk_bf16_f32 v31, v31, v31
	s_add_u32 s8, s28, 0xc000
	s_addc_u32 s9, s29, 0
	global_store_short v235, v12, s[8:9] offset:0
	global_store_short v235, v28, s[8:9] offset:64
	global_store_short v235, v13, s[8:9] offset:2048
	global_store_short v235, v29, s[8:9] offset:2112
	s_add_u32 s8, s28, 0xd000
	s_addc_u32 s9, s29, 0
	global_store_short v235, v14, s[8:9] offset:0
	global_store_short v235, v30, s[8:9] offset:64
	global_store_short v235, v15, s[8:9] offset:2048
	global_store_short v235, v31, s[8:9] offset:2112
	s_add_i32 s12, s12, s33
	s_cmpk_lt_u32 s12, 0x200
	s_cbranch_scc1 .Lat_item
	s_branch .Lat_done
